# scan loop: norm weights hoisted, entry-only waits moved to preheader, exact vmcnt counts via unconditional prefetch (on top of EpiR + attention tail batching)
# baseline (speedup 1.0000x reference)
; DI unsigned pk2(float lo, float hi) { const f32x2 v = {lo, hi}; const bf16x2_t b = __builtin_convertvector(v, bf16x2_t); return __builtin_bit_cast(unsigned, b); }
; template <int C> DI void gdn_scan_item(const Params& p, int l, int b, int h, unsigned char* smem) {
;     ...
;     f32x4 S[8];
;     float* sout = SMP ? p.out + O_STS + (size_t)((l * 8 + b) * 4 + h) * 16384 : p.out + O_STP + (size_t)((l * 4 + b) * 4 + h) * 16384;
;     if (SMP) { const float* s0 = p.in[4] + (size_t)((l * 8 + b) * 4 + h) * 16384;
; #pragma unroll
;         for (int c = 0; c < 8; ++c)
; #pragma unroll
;             for (int r = 0; r < 4; ++r) S[c][r] = s0[(16 * w + 4 * gq + r) * 128 + 16 * c + l15]; }
;     else {
; #pragma unroll
;         for (int c = 0; c < 8; ++c) S[c] = (f32x4){0.f, 0.f, 0.f, 0.f}; }
; #pragma unroll
;     for (int c = 0; c < 8; ++c) { u32x2 o; o.x = pk2(S[c][0], S[c][1]); o.y = pk2(S[c][2], S[c][3]); *(u32x2*)(SbT + (16 * c + l15) * 144 + 16 * w + 4 * gq) = o; }
;     __syncthreads();
;     const int nch = SMP ? 1 : 64;
;     bf16x8 cW[4], cQ[4]; float cU[TPW][4];
;     ...
;     { SCAN_PTRS(0)
; #pragma unroll
;       for (int s = 0; s < 4; ++s) { cW[s] = *(const bf16x8*)(Wo + (16 * ti + l15) * 128 + 32 * s + 8 * gq); cQ[s] = *(const bf16x8*)(QG + (16 * ti + l15) * 128 + 32 * s + 8 * gq); }
; #pragma unroll
;       for (int t = 0; t < TPW; ++t)
; #pragma unroll
;           for (int r = 0; r < 4; ++r) cU[t][r] = U[(16 * ti + 4 * gq + r) * 128 + 16 * (dvg * TPW + t) + l15]; }
.LBB0_677:
	s_or_b64 exec, exec, s[0:1]
	v_readlane_b32 s0, v253, 16
	v_readlane_b32 s1, v253, 17
	s_lshl_b32 s76, s43, 7
	s_and_b64 vcc, exec, s[0:1]
	s_waitcnt lgkmcnt(0)
	s_barrier
	s_cbranch_vccz .LBB0_685
	v_readlane_b32 s0, v254, 47
	v_readlane_b32 s1, v254, 48
	s_load_dwordx2 s[4:5], s[0:1], 0x78
	s_load_dwordx4 s[8:11], s[0:1], 0xd0
	v_mov_b32_e32 v0, v143
	s_lshl_b64 s[0:1], s[76:77], 2
	v_ashrrev_i32_e32 v145, 6, v0
	v_lshrrev_b32_e32 v1, 30, v145
	v_bfe_u32 v153, v0, 4, 2
	v_add_u32_e32 v1, v145, v1
	v_and_b32_e32 v151, 15, v0
	s_waitcnt lgkmcnt(0)
	s_add_u32 s12, s4, s0
	v_lshlrev_b32_e32 v2, 5, v145
	v_lshlrev_b32_e32 v0, 3, v153
	s_mov_b32 s0, 0
	v_ashrrev_i32_e32 v10, 2, v1
	s_addc_u32 s13, s5, s1
	v_add3_u32 v16, 0, v2, v0
	s_movk_i32 s17, 0x120
	s_mov_b32 s1, s0
	v_mul_i32_i24_e32 v14, 4, v10
	v_mad_u32_u24 v4, v151, s17, v16
	v_mov_b64_e32 v[2:3], s[0:1]
	s_add_u32 s1, s10, 0xc101000
	v_sub_u32_e32 v15, v145, v14
	ds_write2st64_b64 v4, v[2:3], v[2:3] offset1:9
	ds_write2st64_b64 v4, v[2:3], v[2:3] offset0:18 offset1:27
	ds_write2st64_b64 v4, v[2:3], v[2:3] offset0:36 offset1:45
	ds_write2st64_b64 v4, v[2:3], v[2:3] offset0:54 offset1:63
	s_addc_u32 s16, s11, 0
	v_readlane_b32 s14, v254, 1
	v_lshlrev_b32_e32 v2, 7, v151
	v_readlane_b32 s15, v254, 2
	s_add_u32 s4, s1, s14
	v_lshl_or_b32 v112, v15, 11, v2
	s_addc_u32 s5, s16, s15
	v_ashrrev_i32_e32 v113, 31, v112
	v_lshl_add_u64 v[2:3], v[112:113], 1, s[4:5]
	v_lshlrev_b32_e32 v140, 4, v153
	v_lshl_add_u64 v[2:3], v[2:3], 0, v[140:141]
	s_mov_b64 s[6:7], 0x8000
	v_add_co_u32_e32 v8, vcc, s60, v2
	v_lshl_add_u64 v[4:5], v[2:3], 0, s[6:7]
	s_mov_b64 s[6:7], 0xc000
	v_addc_co_u32_e32 v9, vcc, 0, v3, vcc
	v_lshl_add_u64 v[6:7], v[2:3], 0, s[6:7]
	v_add_co_u32_e32 v2, vcc, s82, v2
	s_waitcnt lgkmcnt(0)
	s_barrier
	v_addc_co_u32_e32 v3, vcc, 0, v3, vcc
	global_load_dwordx4 v[104:107], v[8:9], off
	global_load_dwordx4 v[100:103], v[2:3], off
	global_load_dwordx4 v[92:95], v[4:5], off offset:64
	global_load_dwordx4 v[84:87], v[4:5], off offset:128
	global_load_dwordx4 v[88:91], v[6:7], off offset:64
	global_load_dwordx4 v[76:79], v[4:5], off offset:192
	global_load_dwordx4 v[80:83], v[6:7], off offset:128
	global_load_dwordx4 v[72:75], v[6:7], off offset:192
	v_lshlrev_b32_e32 v18, 2, v153
	v_lshlrev_b32_e32 v2, 6, v10
	v_lshl_or_b32 v5, v15, 4, v18
	v_or_b32_e32 v4, v2, v151
	v_lshl_add_u32 v114, v5, 7, v4
	v_or_b32_e32 v19, 1, v5
	v_or_b32_e32 v20, 2, v5
	v_or_b32_e32 v21, 3, v5
	v_ashrrev_i32_e32 v115, 31, v114
	v_lshl_add_u32 v116, v19, 7, v4
	v_lshl_add_u32 v118, v20, 7, v4
	v_lshl_add_u32 v120, v21, 7, v4
	v_lshl_add_u64 v[6:7], v[114:115], 2, s[4:5]
	v_ashrrev_i32_e32 v117, 31, v116
	v_ashrrev_i32_e32 v119, 31, v118
	v_ashrrev_i32_e32 v121, 31, v120
	v_lshl_add_u64 v[8:9], v[116:117], 2, s[4:5]
	v_lshl_add_u64 v[10:11], v[118:119], 2, s[4:5]
	v_lshl_add_u64 v[12:13], v[120:121], 2, s[4:5]
	global_load_dword v168, v[6:7], off
	global_load_dword v169, v[8:9], off
	global_load_dword v164, v[6:7], off offset:64
	global_load_dword v165, v[8:9], off offset:64
	global_load_dword v160, v[6:7], off offset:128
	global_load_dword v161, v[8:9], off offset:128
	global_load_dword v157, v[8:9], off offset:192
	global_load_dword v156, v[6:7], off offset:192
	global_load_dword v170, v[10:11], off
	global_load_dword v171, v[12:13], off
	global_load_dword v166, v[10:11], off offset:64
	global_load_dword v167, v[12:13], off offset:64
	global_load_dword v162, v[10:11], off offset:128
	global_load_dword v163, v[12:13], off offset:128
	global_load_dword v159, v[12:13], off offset:192
	global_load_dword v158, v[10:11], off offset:192
	v_lshlrev_b32_e32 v3, 5, v15
	v_and_b32_e32 v10, 64, v205
	v_add3_u32 v9, 0, v3, v0
	v_xor_b32_e32 v3, 1, v205
	v_add_u32_e32 v10, 64, v10
	v_cmp_lt_i32_e32 vcc, v3, v10
	v_readlane_b32 s4, v253, 19
	s_lshl_b32 s4, s4, 1
	v_cndmask_b32_e32 v3, v205, v3, vcc
	v_lshlrev_b32_e32 v172, 2, v3
	v_xor_b32_e32 v3, 2, v205
	v_cmp_lt_i32_e32 vcc, v3, v10
	s_add_u32 s4, s10, s4
	v_lshlrev_b32_e32 v6, 1, v151
	v_cndmask_b32_e32 v3, v205, v3, vcc
	v_lshlrev_b32_e32 v173, 2, v3
	v_xor_b32_e32 v3, 4, v205
	v_cmp_lt_i32_e32 vcc, v3, v10
	v_mov_b32_e32 v7, v141
	s_addc_u32 s5, s11, 0
	v_cndmask_b32_e32 v3, v205, v3, vcc
	v_lshlrev_b32_e32 v174, 2, v3
	v_xor_b32_e32 v3, 8, v205
	v_cmp_lt_i32_e32 vcc, v3, v10
	v_lshl_add_u64 v[6:7], s[4:5], 0, v[6:7]
	v_and_b32_e32 v1, -4, v1
	v_cndmask_b32_e32 v3, v205, v3, vcc
	v_lshlrev_b32_e32 v175, 2, v3
	v_ashrrev_i32_e32 v3, 31, v2
	v_lshl_add_u64 v[2:3], v[2:3], 1, v[6:7]
	s_mov_b64 s[18:19], 0x19441c00
	v_lshlrev_b32_e32 v178, 4, v5
	v_ashrrev_i32_e32 v5, 31, v4
	v_lshlrev_b32_e32 v8, 6, v151
	v_add_u32_e32 v176, 0, v1
	v_lshl_add_u64 v[122:123], v[2:3], 0, s[18:19]
	v_mul_lo_u32 v1, v4, s17
	s_movk_i32 s17, 0xa0
	v_lshl_add_u64 v[2:3], v[4:5], 1, s[4:5]
	s_mov_b64 s[4:5], 0x5f81400
	v_mul_lo_u32 v177, v4, s17
	v_lshl_add_u64 v[124:125], v[4:5], 2, s[12:13]
	v_lshl_add_u64 v[126:127], v[2:3], 0, s[4:5]
	v_lshlrev_b32_e32 v2, 4, v145
	v_readlane_b32 s4, v253, 18
	v_lshl_or_b32 v4, v145, 10, v8
	v_lshlrev_b32_e32 v5, 10, v14
	v_add3_u32 v2, s4, v2, v18
	v_lshlrev_b32_e32 v3, 4, v14
	v_sub_u32_e32 v6, v4, v5
	v_mul_u32_u24_e32 v17, 0x120, v151
	v_add_u32_e32 v155, 0, v140
	v_mul_u32_u24_e32 v10, 0xa0, v151
	v_sub_u32_e32 v182, v2, v3
	v_lshl_add_u64 v[2:3], s[14:15], 0, v[140:141]
	v_ashrrev_i32_e32 v7, 31, v6
	v_ashrrev_i32_e32 v5, 31, v4
	v_lshlrev_b32_e32 v179, 4, v19
	v_lshlrev_b32_e32 v180, 4, v20
	v_lshlrev_b32_e32 v181, 4, v21
	v_lshl_add_u64 v[128:129], v[6:7], 1, v[2:3]
	v_lshl_add_u64 v[130:131], v[4:5], 1, v[2:3]
	v_mov_b32_e32 v32, 0
	v_lshlrev_b32_e32 v140, 1, v0
	v_add_u32_e32 v183, v155, v1
	v_add_u32_e32 v184, v9, v177
	v_add_u32_e32 v185, v155, v10
	v_add_u32_e32 v186, v16, v17
	v_readlane_b32 s12, v254, 26
	s_waitcnt vmcnt(18)
; #define MFMA16(a, b, c) __builtin_amdgcn_mfma_f32_16x16x32_bf16((a), (b), (c), 0, 0, 0)
; DI unsigned pk2(float lo, float hi) { const f32x2 v = {lo, hi}; const bf16x2_t b = __builtin_convertvector(v, bf16x2_t); return __builtin_bit_cast(unsigned, b); }
; template <int C> DI void gdn_scan_item(const Params& p, int l, int b, int h, unsigned char* smem) {
;     ...
;     { SCAN_PTRS(0)
; #pragma unroll
;       for (int s = 0; s < 4; ++s) { cW[s] = *(const bf16x8*)(Wo + (16 * ti + l15) * 128 + 32 * s + 8 * gq); cQ[s] = *(const bf16x8*)(QG + (16 * ti + l15) * 128 + 32 * s + 8 * gq); }
; #pragma unroll
;       for (int t = 0; t < TPW; ++t)
; #pragma unroll
;           for (int r = 0; r < 4; ++r) cU[t][r] = U[(16 * ti + 4 * gq + r) * 128 + 16 * (dvg * TPW + t) + l15]; }
;     ...
; #pragma unroll
;         for (int c = 0; c < 8; ++c) S[c] = S[c] * eg;
; #pragma unroll
;         for (int s = 0; s < KS2; ++s) {
; #pragma unroll
;             for (int c = 0; c < 8; ++c) { const bf16x8 bb = *(const bf16x8*)(VnT + (16 * c + l15) * 80 + 32 * s + 8 * gq); S[c] = MFMA16(aT[s], bb, S[c]); } }
; #pragma unroll
;         for (int c = 0; c < 8; ++c) { u32x2 o; o.x = pk2(S[c][0], S[c][1]); o.y = pk2(S[c][2], S[c][3]); *(u32x2*)(SbT + (16 * c + l15) * 144 + 16 * w + 4 * gq) = o; }
	v_mov_b64_e32 v[12:13], v[76:77]
	v_mov_b64_e32 v[8:9], v[84:85]
	v_mov_b64_e32 v[4:5], v[92:93]
	v_mov_b64_e32 v[0:1], v[104:105]
	s_waitcnt vmcnt(16)
	v_mov_b64_e32 v[24:25], v[72:73]
	v_mov_b64_e32 v[28:29], v[80:81]
	v_mov_b64_e32 v[20:21], v[88:89]
	v_mov_b64_e32 v[16:17], v[100:101]
	v_cmp_eq_u32_e64 s[6:7], 0, v151
	v_readlane_b32 s13, v254, 27
	v_readlane_b32 s17, v254, 5
	v_mov_b32_e32 v33, v32
	v_mov_b32_e32 v34, v32
	v_mov_b32_e32 v35, v32
	v_mov_b32_e32 v36, v32
	v_mov_b32_e32 v37, v32
	v_mov_b32_e32 v38, v32
	v_mov_b32_e32 v39, v32
	v_mov_b32_e32 v40, v32
	v_mov_b32_e32 v41, v32
	v_mov_b32_e32 v42, v32
	v_mov_b32_e32 v43, v32
	v_mov_b32_e32 v44, v32
	v_mov_b32_e32 v45, v32
	v_mov_b32_e32 v46, v32
	v_mov_b32_e32 v47, v32
	v_mov_b32_e32 v48, v32
	v_mov_b32_e32 v49, v32
	v_mov_b32_e32 v50, v32
	v_mov_b32_e32 v51, v32
	v_mov_b32_e32 v52, v32
	v_mov_b32_e32 v53, v32
	v_mov_b32_e32 v54, v32
	v_mov_b32_e32 v55, v32
	v_mov_b32_e32 v56, v32
	v_mov_b32_e32 v57, v32
	v_mov_b32_e32 v58, v32
	v_mov_b32_e32 v59, v32
	v_mov_b32_e32 v60, v32
	v_mov_b32_e32 v61, v32
	v_mov_b32_e32 v62, v32
	v_mov_b32_e32 v63, v32
	v_mov_b64_e32 v[14:15], v[78:79]
	v_mov_b64_e32 v[10:11], v[86:87]
	v_mov_b64_e32 v[6:7], v[94:95]
	v_mov_b64_e32 v[2:3], v[106:107]
	v_mov_b64_e32 v[26:27], v[74:75]
	v_mov_b64_e32 v[30:31], v[82:83]
	v_mov_b64_e32 v[22:23], v[90:91]
	v_mov_b64_e32 v[18:19], v[102:103]
	global_load_dword v144, v[124:125], off
	global_load_dword v204, v[124:125], off offset:64
	global_load_dword v227, v[124:125], off offset:128
	global_load_dword v124, v[124:125], off offset:192
	s_waitcnt vmcnt(0)
	s_branch .LBB0_680
.LBB0_679:
	s_or_b64 exec, exec, s[14:15]
	s_waitcnt lgkmcnt(2)
	ds_read_b128 v[88:91], v185 offset:36864
	v_pk_mul_f32 v[34:35], v[34:35], v[154:155] op_sel_hi:[1,0]
	v_pk_mul_f32 v[32:33], v[32:33], v[154:155] op_sel_hi:[1,0]
	v_pk_mul_f32 v[38:39], v[38:39], v[154:155] op_sel_hi:[1,0]
	v_pk_mul_f32 v[36:37], v[36:37], v[154:155] op_sel_hi:[1,0]
	s_waitcnt vmcnt(41) lgkmcnt(0)
	v_mfma_f32_16x16x32_bf16 v[32:35], v[68:71], v[88:91], v[32:35]
	ds_read_b128 v[88:91], v185 offset:39424
	v_pk_mul_f32 v[42:43], v[42:43], v[154:155] op_sel_hi:[1,0]
	v_pk_mul_f32 v[40:41], v[40:41], v[154:155] op_sel_hi:[1,0]
	v_pk_mul_f32 v[46:47], v[46:47], v[154:155] op_sel_hi:[1,0]
	s_waitcnt lgkmcnt(0)
	v_mfma_f32_16x16x32_bf16 v[36:39], v[68:71], v[88:91], v[36:39]
	ds_read_b128 v[88:91], v185 offset:41984
	v_pk_mul_f32 v[44:45], v[44:45], v[154:155] op_sel_hi:[1,0]
	v_pk_mul_f32 v[50:51], v[50:51], v[154:155] op_sel_hi:[1,0]
	s_waitcnt lgkmcnt(0)
	v_mfma_f32_16x16x32_bf16 v[40:43], v[68:71], v[88:91], v[40:43]
	ds_read_b128 v[88:91], v185 offset:44544
	v_pk_mul_f32 v[48:49], v[48:49], v[154:155] op_sel_hi:[1,0]
	v_pk_mul_f32 v[54:55], v[54:55], v[154:155] op_sel_hi:[1,0]
	s_waitcnt lgkmcnt(0)
	v_mfma_f32_16x16x32_bf16 v[44:47], v[68:71], v[88:91], v[44:47]
	ds_read_b128 v[88:91], v185 offset:47104
	v_pk_mul_f32 v[52:53], v[52:53], v[154:155] op_sel_hi:[1,0]
	v_pk_mul_f32 v[58:59], v[58:59], v[154:155] op_sel_hi:[1,0]
	s_waitcnt lgkmcnt(0)
	v_mfma_f32_16x16x32_bf16 v[48:51], v[68:71], v[88:91], v[48:51]
	ds_read_b128 v[88:91], v185 offset:49664
	v_pk_mul_f32 v[56:57], v[56:57], v[154:155] op_sel_hi:[1,0]
	v_pk_mul_f32 v[62:63], v[62:63], v[154:155] op_sel_hi:[1,0]
	s_waitcnt lgkmcnt(0)
	v_mfma_f32_16x16x32_bf16 v[52:55], v[68:71], v[88:91], v[52:55]
	ds_read_b128 v[88:91], v185 offset:52224
	v_pk_mul_f32 v[60:61], v[60:61], v[154:155] op_sel_hi:[1,0]
	s_mov_b32 s4, 0x358637bd
	s_waitcnt lgkmcnt(0)
	v_mfma_f32_16x16x32_bf16 v[56:59], v[68:71], v[88:91], v[56:59]
	ds_read_b128 v[88:91], v185 offset:54784
	s_add_i32 s0, s0, 64
	s_add_i32 s17, s17, 1
	s_waitcnt lgkmcnt(0)
	v_mfma_f32_16x16x32_bf16 v[60:63], v[68:71], v[88:91], v[60:63]
	ds_read_b128 v[68:71], v185 offset:36928
	ds_read_b128 v[88:91], v185 offset:39488
	s_add_u32 s12, s12, 4
	s_addc_u32 s13, s13, 0
	s_waitcnt vmcnt(40) lgkmcnt(1)
	v_mfma_f32_16x16x32_bf16 v[32:35], v[64:67], v[68:71], v[32:35]
	ds_read_b128 v[68:71], v185 offset:42048
	ds_read_b128 v[92:95], v185 offset:44608
	ds_read_b128 v[96:99], v185 offset:47168
	s_cmpk_lg_i32 s0, 0x1000
	s_waitcnt vmcnt(7)
	v_mov_b32_e32 v170, v197
	s_waitcnt lgkmcnt(3)
	v_mfma_f32_16x16x32_bf16 v[36:39], v[64:67], v[88:91], v[36:39]
	ds_read_b128 v[88:91], v185 offset:49728
	ds_read_b128 v[100:103], v185 offset:52288
	ds_read_b128 v[104:107], v185 offset:54848
	s_waitcnt vmcnt(6)
	v_mov_b32_e32 v171, v198
	v_mov_b32_e32 v168, v187
	s_waitcnt lgkmcnt(5)
	v_mfma_f32_16x16x32_bf16 v[40:43], v[64:67], v[68:71], v[40:43]
	v_cvt_pk_bf16_f32 v68, v32, v33
	v_cvt_pk_bf16_f32 v69, v34, v35
	v_cvt_pk_bf16_f32 v70, v36, v37
	s_waitcnt lgkmcnt(4)
	v_mfma_f32_16x16x32_bf16 v[44:47], v[64:67], v[92:95], v[44:47]
	v_cvt_pk_bf16_f32 v71, v38, v39
	ds_write2st64_b64 v186, v[68:69], v[70:71] offset1:9
	s_nop 0
	v_cvt_pk_bf16_f32 v68, v40, v41
	s_waitcnt lgkmcnt(4)
	v_mfma_f32_16x16x32_bf16 v[48:51], v[64:67], v[96:99], v[48:51]
	v_cvt_pk_bf16_f32 v69, v42, v43
	s_nop 0
	v_cvt_pk_bf16_f32 v70, v44, v45
	v_cvt_pk_bf16_f32 v71, v46, v47
	s_waitcnt lgkmcnt(3)
	v_mfma_f32_16x16x32_bf16 v[52:55], v[64:67], v[88:91], v[52:55]
	ds_write2st64_b64 v186, v[68:69], v[70:71] offset0:18 offset1:27
	s_nop 0
	v_cvt_pk_bf16_f32 v68, v48, v49
	v_cvt_pk_bf16_f32 v69, v50, v51
	s_waitcnt lgkmcnt(3)
	v_mfma_f32_16x16x32_bf16 v[56:59], v[64:67], v[100:103], v[56:59]
	v_lshlrev_b32_e32 v96, 16, v226
	s_nop 0
	v_cvt_pk_bf16_f32 v70, v52, v53
	v_cvt_pk_bf16_f32 v71, v54, v55
	s_waitcnt lgkmcnt(2)
	v_mfma_f32_16x16x32_bf16 v[60:63], v[64:67], v[104:107], v[60:63]
	ds_write2st64_b64 v186, v[68:69], v[70:71] offset0:36 offset1:45
	s_nop 0
	v_cvt_pk_bf16_f32 v64, v56, v57
	v_cvt_pk_bf16_f32 v65, v58, v59
	v_add_u32_e32 v68, 0, v179
	v_add_u32_e32 v70, 0, v180
	s_nop 1
	v_cvt_pk_bf16_f32 v66, v60, v61
	v_cvt_pk_bf16_f32 v67, v62, v63
	ds_write2st64_b64 v186, v[64:65], v[66:67] offset0:54 offset1:63
	s_waitcnt lgkmcnt(0)
	s_barrier
; DI float bf2f(unsigned short b) { return __uint_as_float(((unsigned)b) << 16); }
; DI unsigned short f2bf(float f) { unsigned u = __float_as_uint(f); u += 0x7fffu + ((u >> 16) & 1u); return (unsigned short)(u >> 16); }
; template <int C> DI void gdn_scan_item(const Params& p, int l, int b, int h, unsigned char* smem) {
;     ...
;         __syncthreads();
; #pragma unroll
;         for (int r = 0; r < 4; ++r) { const int i = 16 * ti + 4 * gq + r; float tot = 0.f;
; #pragma unroll
;             for (int d = 0; d < NDVG; ++d) tot += RS[i * 4 + d];
;             const float rs = rsqrtf(tot * (1.0f / 128.0f) + EPS);
; #pragma unroll
;             for (int t = 0; t < TPW; ++t) { const int dv = 16 * (dvg * TPW + t) + l15; const float sz = bf2f(szr[t][r]);
;                 MIX[(size_t)(r0c + i) * KOUT + 512 + h * 128 + dv] = f2bf(a2[t][r] * rs * nw[dv] * sz); } }
; #pragma unroll
;         for (int s = 0; s < 4; ++s) { cW[s] = nW[s]; cQ[s] = nQ[s]; }
; #pragma unroll
;         for (int t = 0; t < TPW; ++t)
; #pragma unroll
;             for (int r = 0; r < 4; ++r) cU[t][r] = nU[t][r];
	v_add_u32_e32 v66, 0, v178
	ds_read_b64 v[66:67], v66 offset:57344
	ds_read_b64 v[68:69], v68 offset:57344
	v_lshl_add_u64 v[64:65], v[126:127], 0, v[138:139]
	v_add_u32_e32 v88, 0, v181
	ds_read_b64 v[70:71], v70 offset:57344
	ds_read_b64 v[88:89], v88 offset:57344
	s_waitcnt lgkmcnt(3)
	v_mov_b32_e32 v91, v66
	s_waitcnt lgkmcnt(2)
	v_mov_b32_e32 v90, v68
	v_pk_add_f32 v[90:91], v[90:91], 0 op_sel_hi:[1,0]
	v_mov_b32_e32 v66, v69
	v_pk_add_f32 v[66:67], v[90:91], v[66:67]
	v_mov_b64_e32 v[68:69], s[4:5]
	s_brev_b32 s4, 60
	v_pk_fma_f32 v[66:67], v[66:67], s[4:5], v[68:69] op_sel_hi:[1,0,0]
	v_lshlrev_b32_e32 v91, 16, v224
	v_mul_f32_e32 v90, 0x4b800000, v67
	v_cmp_gt_f32_e32 vcc, s79, v67
	v_lshlrev_b32_e32 v97, 16, v225
	v_mov_b64_e32 v[102:103], v[18:19]
	v_cndmask_b32_e32 v67, v67, v90, vcc
	v_rsq_f32_e32 v67, v67
	v_lshlrev_b32_e32 v90, 16, v223
	v_mov_b64_e32 v[106:107], v[2:3]
	v_mov_b64_e32 v[100:101], v[16:17]
	v_mul_f32_e32 v98, 0x45800000, v67
	v_cndmask_b32_e32 v67, v67, v98, vcc
	v_mul_f32_e32 v72, v72, v67
	v_cmp_gt_f32_e32 vcc, s79, v66
	v_mov_b64_e32 v[104:105], v[0:1]
	v_mov_b32_e32 v169, v188
	s_waitcnt vmcnt(5)
	v_mov_b32_e32 v166, v199
	s_waitcnt vmcnt(4)
	v_mov_b32_e32 v167, v209
	v_mov_b32_e32 v164, v189
	v_mov_b32_e32 v165, v190
	s_waitcnt vmcnt(3)
	v_mov_b32_e32 v162, v210
	s_waitcnt vmcnt(2)
	v_mov_b32_e32 v163, v211
	v_mov_b32_e32 v160, v192
	v_mov_b32_e32 v161, v193
	s_waitcnt vmcnt(0)
	v_mov_b32_e32 v158, v213
	v_mov_b32_e32 v159, v212
	v_mov_b32_e32 v156, v196
	v_mov_b32_e32 v157, v195
	v_mul_f32_e32 v72, v144, v72
	v_mul_f32_e32 v72, v72, v96
	v_bfe_u32 v96, v72, 16, 1
	v_add3_u32 v72, v72, v96, s59
	global_store_short_d16_hi v[64:65], v72, off
	v_mul_f32_e32 v72, v76, v67
	v_mul_f32_e32 v72, v204, v72
	v_mul_f32_e32 v72, v72, v90
	v_bfe_u32 v76, v72, 16, 1
	v_add3_u32 v72, v72, v76, s59
	global_store_short_d16_hi v[64:65], v72, off offset:32
	v_mul_f32_e32 v72, v80, v67
	v_mul_f32_e32 v72, v227, v72
	v_mul_f32_e32 v72, v72, v91
	v_bfe_u32 v76, v72, 16, 1
	v_add3_u32 v72, v72, v76, s59
	global_store_short_d16_hi v[64:65], v72, off offset:64
	v_mul_f32_e32 v72, 0x4b800000, v66
	v_mul_f32_e32 v67, v84, v67
	v_cndmask_b32_e32 v66, v66, v72, vcc
	v_mul_f32_e32 v67, v124, v67
	v_rsq_f32_e32 v66, v66
	v_mul_f32_e32 v67, v67, v97
	v_bfe_u32 v72, v67, 16, 1
	v_add3_u32 v67, v67, v72, s59
	global_store_short_d16_hi v[64:65], v67, off offset:96
	v_mul_f32_e32 v64, 0x45800000, v66
	v_cndmask_b32_e32 v66, v66, v64, vcc
	v_mul_f32_e32 v65, v73, v66
	v_lshlrev_b32_e32 v64, 16, v222
	v_mul_f32_e32 v65, v144, v65
	v_mul_f32_e32 v64, v65, v64
	v_bfe_u32 v65, v64, 16, 1
	v_add3_u32 v67, v64, v65, s59
	v_lshl_add_u64 v[64:65], v[126:127], 0, v[136:137]
	v_mul_f32_e32 v72, v77, v66
	global_store_short_d16_hi v[64:65], v67, off
	v_lshlrev_b32_e32 v67, 16, v221
	v_mul_f32_e32 v72, v204, v72
	v_mul_f32_e32 v67, v72, v67
	v_bfe_u32 v72, v67, 16, 1
	v_add3_u32 v67, v67, v72, s59
	v_mul_f32_e32 v72, v81, v66
	global_store_short_d16_hi v[64:65], v67, off offset:32
	v_lshlrev_b32_e32 v67, 16, v220
	v_mul_f32_e32 v72, v227, v72
	v_mul_f32_e32 v67, v72, v67
	v_bfe_u32 v72, v67, 16, 1
	v_add3_u32 v67, v67, v72, s59
	v_mul_f32_e32 v66, v85, v66
	global_store_short_d16_hi v[64:65], v67, off offset:64
	v_lshlrev_b32_e32 v67, 16, v219
	v_mul_f32_e32 v66, v124, v66
	v_mul_f32_e32 v66, v66, v67
	v_bfe_u32 v67, v66, 16, 1
	v_add3_u32 v66, v66, v67, s59
	global_store_short_d16_hi v[64:65], v66, off offset:96
	s_waitcnt lgkmcnt(0)
	v_mov_b32_e32 v66, v88
	v_mov_b32_e32 v67, v70
	v_pk_add_f32 v[66:67], v[66:67], 0 op_sel_hi:[1,0]
	v_mov_b32_e32 v70, v89
	v_pk_add_f32 v[66:67], v[66:67], v[70:71]
	v_lshlrev_b32_e32 v72, 16, v218
	v_pk_fma_f32 v[66:67], v[66:67], s[4:5], v[68:69] op_sel_hi:[1,0,0]
	v_lshl_add_u64 v[64:65], v[126:127], 0, v[134:135]
	v_mul_f32_e32 v68, 0x4b800000, v67
	v_cmp_gt_f32_e32 vcc, s79, v67
	v_lshlrev_b32_e32 v69, 16, v216
	v_lshlrev_b32_e32 v70, 16, v217
	v_cndmask_b32_e32 v67, v67, v68, vcc
	v_rsq_f32_e32 v67, v67
	v_lshlrev_b32_e32 v68, 16, v215
	s_mov_b64 s[4:5], 0x16000
	v_mov_b64_e32 v[90:91], v[22:23]
	v_mul_f32_e32 v71, 0x45800000, v67
	v_cndmask_b32_e32 v67, v67, v71, vcc
	v_mul_f32_e32 v71, v74, v67
	v_mul_f32_e32 v71, v144, v71
	v_mul_f32_e32 v71, v71, v72
	v_bfe_u32 v72, v71, 16, 1
	v_add3_u32 v71, v71, v72, s59
	global_store_short_d16_hi v[64:65], v71, off
	v_mul_f32_e32 v71, v78, v67
	v_mul_f32_e32 v71, v204, v71
	v_mul_f32_e32 v68, v71, v68
	v_bfe_u32 v71, v68, 16, 1
	v_add3_u32 v68, v68, v71, s59
	global_store_short_d16_hi v[64:65], v68, off offset:32
	v_mul_f32_e32 v68, v82, v67
	v_mul_f32_e32 v68, v227, v68
	v_mul_f32_e32 v68, v68, v69
	v_bfe_u32 v69, v68, 16, 1
	v_add3_u32 v68, v68, v69, s59
	global_store_short_d16_hi v[64:65], v68, off offset:64
	v_mul_f32_e32 v68, 0x4b800000, v66
	v_cmp_gt_f32_e32 vcc, s79, v66
	v_mul_f32_e32 v67, v86, v67
	v_mul_f32_e32 v67, v124, v67
	v_cndmask_b32_e32 v66, v66, v68, vcc
	v_rsq_f32_e32 v66, v66
	v_mul_f32_e32 v67, v67, v70
	v_bfe_u32 v68, v67, 16, 1
	v_add3_u32 v67, v67, v68, s59
	global_store_short_d16_hi v[64:65], v67, off offset:96
	v_mul_f32_e32 v64, 0x45800000, v66
	v_cndmask_b32_e32 v66, v66, v64, vcc
	v_mul_f32_e32 v65, v75, v66
	v_lshlrev_b32_e32 v64, 16, v214
	v_mul_f32_e32 v65, v144, v65
	v_mul_f32_e32 v64, v65, v64
	v_bfe_u32 v65, v64, 16, 1
	v_add3_u32 v67, v64, v65, s59
	v_lshl_add_u64 v[64:65], v[126:127], 0, v[132:133]
	v_mul_f32_e32 v68, v79, v66
	global_store_short_d16_hi v[64:65], v67, off
	v_lshlrev_b32_e32 v67, 16, v208
	v_mul_f32_e32 v68, v204, v68
	v_mul_f32_e32 v67, v68, v67
	v_bfe_u32 v68, v67, 16, 1
	v_add3_u32 v67, v67, v68, s59
	v_mul_f32_e32 v68, v83, v66
	global_store_short_d16_hi v[64:65], v67, off offset:32
	v_lshlrev_b32_e32 v67, 16, v194
	v_mul_f32_e32 v68, v227, v68
	v_mul_f32_e32 v67, v68, v67
	v_bfe_u32 v68, v67, 16, 1
	v_add3_u32 v67, v67, v68, s59
	v_mul_f32_e32 v66, v87, v66
	global_store_short_d16_hi v[64:65], v67, off offset:64
	v_lshlrev_b32_e32 v67, 16, v191
	v_mul_f32_e32 v66, v124, v66
	v_mul_f32_e32 v66, v66, v67
	v_bfe_u32 v67, v66, 16, 1
	v_mov_b64_e32 v[82:83], v[30:31]
	v_mov_b64_e32 v[74:75], v[26:27]
	v_mov_b64_e32 v[94:95], v[6:7]
	v_mov_b64_e32 v[86:87], v[10:11]
	v_mov_b64_e32 v[78:79], v[14:15]
	v_add3_u32 v66, v66, v67, s59
	v_lshl_add_u64 v[128:129], v[128:129], 0, s[4:5]
	v_lshl_add_u64 v[130:131], v[130:131], 0, s[4:5]
	v_mov_b64_e32 v[88:89], v[20:21]
	v_mov_b64_e32 v[80:81], v[28:29]
	v_mov_b64_e32 v[72:73], v[24:25]
	v_mov_b64_e32 v[92:93], v[4:5]
	v_mov_b64_e32 v[84:85], v[8:9]
	v_mov_b64_e32 v[76:77], v[12:13]
	global_store_short_d16_hi v[64:65], v66, off offset:96
	s_cbranch_scc0 .LBB0_684
; template <int C> DI void gdn_scan_item(const Params& p, int l, int b, int h, unsigned char* smem) {
;     ...
;         bf16x8 aK[KS2], aT[KS2]; unsigned short szr[TPW][4]; float eg; int r0c;
;         { SCAN_PTRS(n) r0c = r0; eg = ((const float*)(ws + WS_EG))[ci];
; #pragma unroll
;           for (int s = 0; s < KS2; ++s) { aK[s] = *(const bf16x8*)(QKM + (16 * ti + l15) * C + 32 * s + 8 * gq); aT[s] = *(const bf16x8*)(KDT + (16 * w + l15) * C + 32 * s + 8 * gq); }
; #pragma unroll
;           for (int t = 0; t < TPW; ++t)
; #pragma unroll
;               for (int r = 0; r < 4; ++r) szr[t][r] = QZ[(size_t)(r0 + 16 * ti + 4 * gq + r) * NQZ + 1536 + h * 128 + 16 * (dvg * TPW + t) + l15]; }
;         bf16x8 nW[4], nQ[4]; float nU[TPW][4];
;         if (n + 1 < nch) { SCAN_PTRS(n + 1)
; #pragma unroll
;           for (int s = 0; s < 4; ++s) { nW[s] = *(const bf16x8*)(Wo + (16 * ti + l15) * 128 + 32 * s + 8 * gq); nQ[s] = *(const bf16x8*)(QG + (16 * ti + l15) * 128 + 32 * s + 8 * gq); }
; #pragma unroll
;           for (int t = 0; t < TPW; ++t)
; #pragma unroll
;               for (int r = 0; r < 4; ++r) nU[t][r] = U[(16 * ti + 4 * gq + r) * 128 + 16 * (dvg * TPW + t) + l15]; }
.LBB0_680:
	s_add_u32 s4, s10, s12
	v_add_u32_e32 v132, s0, v182
	s_addc_u32 s5, s11, s13
	v_add_u32_e32 v134, 1, v132
	global_load_dword v154, v141, s[4:5]
	v_lshl_add_u64 v[64:65], s[10:11], 0, v[128:129]
	s_mov_b32 s4, 0xc115000
	v_ashrrev_i32_e32 v133, 31, v132
	v_ashrrev_i32_e32 v135, 31, v134
	v_add_co_u32_e32 v64, vcc, s4, v64
	v_lshlrev_b64 v[138:139], 12, v[132:133]
	v_lshlrev_b64 v[136:137], 12, v[134:135]
	v_add_u32_e32 v134, 2, v132
	v_add_u32_e32 v132, 3, v132
	v_lshl_add_u64 v[66:67], s[10:11], 0, v[130:131]
	v_addc_co_u32_e32 v65, vcc, 0, v65, vcc
	s_mov_b32 s4, 0xc111000
	v_ashrrev_i32_e32 v133, 31, v132
	v_add_co_u32_e32 v66, vcc, s4, v66
	v_ashrrev_i32_e32 v135, 31, v134
	v_lshlrev_b64 v[132:133], 12, v[132:133]
	v_addc_co_u32_e32 v67, vcc, 0, v67, vcc
	v_lshl_add_u64 v[146:147], v[122:123], 0, v[138:139]
	v_lshlrev_b64 v[134:135], 12, v[134:135]
	v_lshl_add_u64 v[190:191], v[122:123], 0, v[132:133]
	global_load_dwordx4 v[108:111], v[64:65], off
	global_load_dwordx4 v[96:99], v[64:65], off offset:64
	global_load_dwordx4 v[68:71], v[66:67], off
	s_nop 0
	global_load_dwordx4 v[64:67], v[66:67], off offset:64
	v_lshl_add_u64 v[148:149], v[122:123], 0, v[136:137]
	v_lshl_add_u64 v[188:189], v[122:123], 0, v[134:135]
	global_load_ushort v226, v[146:147], off
	global_load_ushort v222, v[148:149], off
	global_load_ushort v223, v[146:147], off offset:32
	global_load_ushort v221, v[148:149], off offset:32
	global_load_ushort v224, v[146:147], off offset:64
	global_load_ushort v220, v[148:149], off offset:64
	global_load_ushort v219, v[148:149], off offset:96
	global_load_ushort v225, v[146:147], off offset:96
	global_load_ushort v218, v[188:189], off
	global_load_ushort v214, v[190:191], off
	global_load_ushort v215, v[188:189], off offset:32
	global_load_ushort v208, v[190:191], off offset:32
	global_load_ushort v216, v[188:189], off offset:64
	global_load_ushort v194, v[190:191], off offset:64
	s_nop 0
	global_load_ushort v191, v[190:191], off offset:96
	s_nop 0
	global_load_ushort v217, v[188:189], off offset:96
	s_cmpk_eq_i32 s0, 0xfc0
	v_mov_b32_e32 v197, v170
	v_mov_b32_e32 v198, v171
	v_mov_b32_e32 v187, v168
	v_mov_b32_e32 v188, v169
	v_mov_b32_e32 v199, v166
	v_mov_b32_e32 v209, v167
	v_mov_b32_e32 v189, v164
	v_mov_b32_e32 v190, v165
	v_mov_b32_e32 v210, v162
	v_mov_b32_e32 v211, v163
	v_mov_b32_e32 v192, v160
	v_mov_b32_e32 v193, v161
	v_mov_b32_e32 v213, v158
	v_mov_b32_e32 v212, v159
	v_mov_b32_e32 v196, v156
	v_mov_b32_e32 v195, v157
	s_nop 0
	s_mul_i32 s4, s17, 0x16000
	s_mul_hi_i32 s5, s17, 0x16000
	s_add_u32 s4, s1, s4
	s_addc_u32 s5, s16, s5
	v_lshl_add_u64 v[0:1], v[112:113], 1, s[4:5]
	v_lshl_add_u64 v[0:1], v[0:1], 0, v[140:141]
	v_add_co_u32_e32 v2, vcc, 0x8000, v0
	s_mov_b64 s[14:15], 0x8000
	s_nop 0
	v_addc_co_u32_e32 v3, vcc, 0, v1, vcc
	v_lshl_add_u64 v[12:13], v[0:1], 0, s[14:15]
	s_mov_b64 s[14:15], 0xc000
	v_add_co_u32_e32 v4, vcc, 0xc000, v0
	v_lshl_add_u64 v[24:25], v[0:1], 0, s[14:15]
	s_nop 0
	v_addc_co_u32_e32 v5, vcc, 0, v1, vcc
	v_lshl_add_u64 v[146:147], v[114:115], 2, s[4:5]
	v_lshl_add_u64 v[212:213], v[120:121], 2, s[4:5]
	global_load_dwordx4 v[0:3], v[2:3], off
	s_nop 0
	global_load_dwordx4 v[16:19], v[4:5], off
	s_nop 0
	global_load_dwordx4 v[4:7], v[12:13], off offset:64
	global_load_dwordx4 v[8:11], v[12:13], off offset:128
	global_load_dwordx4 v[20:23], v[24:25], off offset:64
	s_nop 0
	global_load_dwordx4 v[12:15], v[12:13], off offset:192
	s_nop 0
	global_load_dwordx4 v[28:31], v[24:25], off offset:128
	s_nop 0
	global_load_dwordx4 v[24:27], v[24:25], off offset:192
	v_lshl_add_u64 v[148:149], v[116:117], 2, s[4:5]
	v_lshl_add_u64 v[228:229], v[118:119], 2, s[4:5]
	global_load_dword v187, v[146:147], off
	global_load_dword v188, v[148:149], off
	global_load_dword v189, v[146:147], off offset:64
	global_load_dword v190, v[148:149], off offset:64
	global_load_dword v192, v[146:147], off offset:128
	global_load_dword v193, v[148:149], off offset:128
	global_load_dword v195, v[148:149], off offset:192
	global_load_dword v196, v[146:147], off offset:192
	global_load_dword v197, v[228:229], off
	global_load_dword v198, v[212:213], off
	global_load_dword v199, v[228:229], off offset:64
	global_load_dword v209, v[212:213], off offset:64
	global_load_dword v210, v[228:229], off offset:128
	global_load_dword v211, v[212:213], off offset:128
	s_nop 0
	global_load_dword v212, v[212:213], off offset:192
	s_nop 0
	global_load_dword v213, v[228:229], off offset:192
; #define MFMA16(a, b, c) __builtin_amdgcn_mfma_f32_16x16x32_bf16((a), (b), (c), 0, 0, 0)
; DI unsigned pk2(float lo, float hi) { const f32x2 v = {lo, hi}; const bf16x2_t b = __builtin_convertvector(v, bf16x2_t); return __builtin_bit_cast(unsigned, b); }
; template <int C> DI void gdn_scan_item(const Params& p, int l, int b, int h, unsigned char* smem) {
;     ...
;         f32x4 a1[TPW], a2[TPW];
; #pragma unroll
;         for (int t = 0; t < TPW; ++t) { a1[t] = (f32x4){0.f, 0.f, 0.f, 0.f}; a2[t] = a1[t]; }
; #pragma unroll
;         for (int s = 0; s < 4; ++s) {
; #pragma unroll
;             for (int t = 0; t < TPW; ++t) { const int c = dvg * TPW + t; const bf16x8 bb = *(const bf16x8*)(SbT + (16 * c + l15) * 144 + 32 * s + 8 * gq); a1[t] = MFMA16(cW[s], bb, a1[t]); a2[t] = MFMA16(cQ[s], bb, a2[t]); } }
; #pragma unroll
;         for (int t = 0; t < TPW; ++t) { const int c = dvg * TPW + t; float vn[4];
; #pragma unroll
;             for (int r = 0; r < 4; ++r) vn[r] = cU[t][r] - a1[t][r];
;             u32x2 o; o.x = pk2(vn[0], vn[1]); o.y = pk2(vn[2], vn[3]); *(u32x2*)(VnT + (16 * c + l15) * 80 + 16 * ti + 4 * gq) = o; }
;         __syncthreads();
.LBB0_682:
	ds_read_b128 v[228:231], v183
	ds_read_b128 v[236:239], v183 offset:4608
	ds_read_b128 v[244:247], v183 offset:9216
	ds_read_b128 v[146:149], v183 offset:13824
	s_waitcnt lgkmcnt(3)
	v_mfma_f32_16x16x32_bf16 v[232:235], v[104:107], v[228:231], 0
	v_mfma_f32_16x16x32_bf16 v[228:231], v[100:103], v[228:231], 0
	s_waitcnt lgkmcnt(2)
	v_mfma_f32_16x16x32_bf16 v[240:243], v[104:107], v[236:239], 0
	v_mfma_f32_16x16x32_bf16 v[236:239], v[100:103], v[236:239], 0
	s_waitcnt lgkmcnt(1)
	v_mfma_f32_16x16x32_bf16 v[248:251], v[104:107], v[244:247], 0
	v_mfma_f32_16x16x32_bf16 v[244:247], v[100:103], v[244:247], 0
	s_waitcnt lgkmcnt(0)
	v_mfma_f32_16x16x32_bf16 v[104:107], v[104:107], v[146:149], 0
	v_mfma_f32_16x16x32_bf16 v[100:103], v[100:103], v[146:149], 0
	ds_read_b128 v[146:149], v183 offset:64
	s_waitcnt lgkmcnt(0)
	v_mfma_f32_16x16x32_bf16 v[232:235], v[92:95], v[146:149], v[232:235]
	v_mfma_f32_16x16x32_bf16 v[146:149], v[88:91], v[146:149], v[228:231]
	s_nop 2
	ds_read_b128 v[228:231], v183 offset:4672
	s_waitcnt lgkmcnt(0)
	v_mfma_f32_16x16x32_bf16 v[240:243], v[92:95], v[228:231], v[240:243]
	v_mfma_f32_16x16x32_bf16 v[228:231], v[88:91], v[228:231], v[236:239]
	s_nop 2
	ds_read_b128 v[236:239], v183 offset:9280
	s_waitcnt lgkmcnt(0)
	v_mfma_f32_16x16x32_bf16 v[248:251], v[92:95], v[236:239], v[248:251]
	v_mfma_f32_16x16x32_bf16 v[236:239], v[88:91], v[236:239], v[244:247]
	s_nop 2
	ds_read_b128 v[244:247], v183 offset:13888
	s_waitcnt lgkmcnt(0)
	v_mfma_f32_16x16x32_bf16 v[88:91], v[88:91], v[244:247], v[100:103]
	s_nop 2
	ds_read_b128 v[100:103], v183 offset:128
	v_mfma_f32_16x16x32_bf16 v[92:95], v[92:95], v[244:247], v[104:107]
	s_waitcnt lgkmcnt(0)
	v_mfma_f32_16x16x32_bf16 v[104:107], v[84:87], v[100:103], v[232:235]
	v_mfma_f32_16x16x32_bf16 v[100:103], v[80:83], v[100:103], v[146:149]
	s_nop 2
	ds_read_b128 v[146:149], v183 offset:4736
	s_waitcnt lgkmcnt(0)
	v_mfma_f32_16x16x32_bf16 v[232:235], v[84:87], v[146:149], v[240:243]
	v_mfma_f32_16x16x32_bf16 v[146:149], v[80:83], v[146:149], v[228:231]
	s_nop 2
	ds_read_b128 v[228:231], v183 offset:9344
	s_waitcnt lgkmcnt(0)
	v_mfma_f32_16x16x32_bf16 v[240:243], v[84:87], v[228:231], v[248:251]
	v_mfma_f32_16x16x32_bf16 v[228:231], v[80:83], v[228:231], v[236:239]
	s_nop 2
	ds_read_b128 v[236:239], v183 offset:13952
	s_waitcnt lgkmcnt(0)
	v_mfma_f32_16x16x32_bf16 v[80:83], v[80:83], v[236:239], v[88:91]
	s_nop 2
	ds_read_b128 v[88:91], v183 offset:192
	v_mfma_f32_16x16x32_bf16 v[84:87], v[84:87], v[236:239], v[92:95]
	s_waitcnt lgkmcnt(0)
	v_mfma_f32_16x16x32_bf16 v[92:95], v[76:79], v[88:91], v[104:107]
	v_mfma_f32_16x16x32_bf16 v[88:91], v[72:75], v[88:91], v[100:103]
	s_nop 2
	ds_read_b128 v[100:103], v183 offset:4800
	s_waitcnt lgkmcnt(0)
	v_mfma_f32_16x16x32_bf16 v[104:107], v[76:79], v[100:103], v[232:235]
	v_mfma_f32_16x16x32_bf16 v[100:103], v[72:75], v[100:103], v[146:149]
	s_nop 2
	ds_read_b128 v[146:149], v183 offset:9408
	s_waitcnt lgkmcnt(0)
	v_mfma_f32_16x16x32_bf16 v[232:235], v[76:79], v[146:149], v[240:243]
	v_mfma_f32_16x16x32_bf16 v[146:149], v[72:75], v[146:149], v[228:231]
	s_nop 2
	ds_read_b128 v[228:231], v183 offset:14016
	s_waitcnt lgkmcnt(0)
	v_mfma_f32_16x16x32_bf16 v[76:79], v[76:79], v[228:231], v[84:87]
	s_nop 2
	v_add_f32_e64 v84, v166, -v106
	v_add_f32_e64 v85, v167, -v107
	s_nop 2
	v_pk_add_f32 v[76:77], v[156:157], v[76:77] neg_lo:[0,1] neg_hi:[0,1]
	v_mfma_f32_16x16x32_bf16 v[72:75], v[72:75], v[228:231], v[80:83]
	v_add_f32_e64 v78, v158, -v78
	v_add_f32_e64 v79, v159, -v79
	v_cvt_pk_bf16_f32 v76, v76, v77
	v_cvt_pk_bf16_f32 v77, v78, v79
	v_pk_add_f32 v[80:81], v[168:169], v[92:93] neg_lo:[0,1] neg_hi:[0,1]
	v_pk_add_f32 v[82:83], v[170:171], v[94:95] neg_lo:[0,1] neg_hi:[0,1]
	v_cvt_pk_bf16_f32 v80, v80, v81
	v_cvt_pk_bf16_f32 v81, v82, v83
	v_pk_add_f32 v[82:83], v[164:165], v[104:105] neg_lo:[0,1] neg_hi:[0,1]
	v_add_u32_e32 v92, v155, v177
	v_cvt_pk_bf16_f32 v82, v82, v83
	v_cvt_pk_bf16_f32 v83, v84, v85
	ds_write2st64_b64 v184, v[80:81], v[82:83] offset0:72 offset1:77
	v_pk_add_f32 v[80:81], v[160:161], v[232:233] neg_lo:[0,1] neg_hi:[0,1]
	v_pk_add_f32 v[82:83], v[162:163], v[234:235] neg_lo:[0,1] neg_hi:[0,1]
	v_cvt_pk_bf16_f32 v80, v80, v81
	v_cvt_pk_bf16_f32 v81, v82, v83
	ds_write2st64_b64 v184, v[80:81], v[76:77] offset0:82 offset1:87
	s_waitcnt lgkmcnt(0)
	s_barrier
; #define MFMA16(a, b, c) __builtin_amdgcn_mfma_f32_16x16x32_bf16((a), (b), (c), 0, 0, 0)
; template <int C> DI void gdn_scan_item(const Params& p, int l, int b, int h, unsigned char* smem) {
;     ...
; #pragma unroll
;         for (int s = 0; s < KS2; ++s) {
; #pragma unroll
;             for (int t = 0; t < TPW; ++t) { const int c = dvg * TPW + t; const bf16x8 bb = *(const bf16x8*)(VnT + (16 * c + l15) * 80 + 32 * s + 8 * gq); a2[t] = MFMA16(aK[s], bb, a2[t]); } }
;         { float ss[4];
; #pragma unroll
;           for (int r = 0; r < 4; ++r) { float q = 0.f;
; #pragma unroll
;               for (int t = 0; t < TPW; ++t) q += a2[t][r] * a2[t][r];
;               q += __shfl_xor(q, 1); q += __shfl_xor(q, 2); q += __shfl_xor(q, 4); q += __shfl_xor(q, 8); ss[r] = q; }
;           if (l15 == 0) {
; #pragma unroll
;               for (int r = 0; r < 4; ++r) RS[(16 * ti + 4 * gq + r) * 4 + dvg] = ss[r]; } }
;     ...
; #pragma unroll
;     for (int c = 0; c < 8; ++c)
; #pragma unroll
;         for (int r = 0; r < 4; ++r) sout[(16 * w + 4 * gq + r) * 128 + 16 * c + l15] = S[c][r];
	ds_read_b128 v[76:79], v92 offset:36864
	ds_read_b128 v[80:83], v92 offset:39424
	s_waitcnt vmcnt(43) lgkmcnt(1)
	v_mfma_f32_16x16x32_bf16 v[76:79], v[108:111], v[76:79], v[88:91]
	s_nop 2
	ds_read_b128 v[88:91], v92 offset:44544
	ds_read_b128 v[84:87], v92 offset:41984
	s_waitcnt lgkmcnt(1)
	v_mfma_f32_16x16x32_bf16 v[88:91], v[108:111], v[88:91], v[72:75]
	s_nop 2
	ds_read_b128 v[72:75], v92 offset:36928
	s_waitcnt vmcnt(42) lgkmcnt(0)
	v_mfma_f32_16x16x32_bf16 v[72:75], v[96:99], v[72:75], v[76:79]
	s_nop 2
	ds_read_b128 v[76:79], v92 offset:39488
	v_mfma_f32_16x16x32_bf16 v[80:83], v[108:111], v[80:83], v[100:103]
	s_waitcnt lgkmcnt(0)
	v_mfma_f32_16x16x32_bf16 v[76:79], v[96:99], v[76:79], v[80:83]
	v_mfma_f32_16x16x32_bf16 v[84:87], v[108:111], v[84:87], v[146:149]
	s_nop 4
	ds_read_b128 v[80:83], v92 offset:42048
	s_nop 0
	v_mul_f32_e32 v94, v79, v79
	v_fmac_f32_e32 v94, v75, v75
	s_waitcnt lgkmcnt(0)
	v_mfma_f32_16x16x32_bf16 v[80:83], v[96:99], v[80:83], v[84:87]
	s_nop 2
	ds_read_b128 v[84:87], v92 offset:44608
	s_waitcnt lgkmcnt(0)
	v_mfma_f32_16x16x32_bf16 v[84:87], v[96:99], v[84:87], v[88:91]
	s_nop 2
	v_mul_f32_e32 v88, v76, v76
	v_mul_f32_e32 v90, v77, v77
	v_mul_f32_e32 v92, v78, v78
	v_fmac_f32_e32 v88, v72, v72
	v_fmac_f32_e32 v90, v73, v73
	v_fmac_f32_e32 v92, v74, v74
	v_fmac_f32_e32 v88, v80, v80
	v_fmac_f32_e32 v90, v81, v81
	v_fmac_f32_e32 v92, v82, v82
	v_fmac_f32_e32 v94, v83, v83
	v_fmac_f32_e32 v88, v84, v84
	v_fmac_f32_e32 v90, v85, v85
	v_fmac_f32_e32 v92, v86, v86
	v_fmac_f32_e32 v94, v87, v87
	ds_bpermute_b32 v89, v172, v88
	ds_bpermute_b32 v91, v172, v90
	ds_bpermute_b32 v93, v172, v92
	ds_bpermute_b32 v95, v172, v94
	s_waitcnt lgkmcnt(3)
	v_add_f32_e32 v88, v88, v89
	s_waitcnt lgkmcnt(2)
	v_add_f32_e32 v90, v90, v91
	s_waitcnt lgkmcnt(1)
	v_add_f32_e32 v92, v92, v93
	s_waitcnt lgkmcnt(0)
	v_add_f32_e32 v94, v94, v95
	ds_bpermute_b32 v89, v173, v88
	ds_bpermute_b32 v91, v173, v90
	ds_bpermute_b32 v93, v173, v92
	ds_bpermute_b32 v95, v173, v94
	s_waitcnt lgkmcnt(3)
	v_add_f32_e32 v88, v88, v89
	s_waitcnt lgkmcnt(2)
	v_add_f32_e32 v90, v90, v91
	s_waitcnt lgkmcnt(1)
	v_add_f32_e32 v92, v92, v93
	s_waitcnt lgkmcnt(0)
	v_add_f32_e32 v94, v94, v95
	ds_bpermute_b32 v89, v174, v88
	ds_bpermute_b32 v91, v174, v90
	ds_bpermute_b32 v93, v174, v92
	ds_bpermute_b32 v95, v174, v94
	s_waitcnt lgkmcnt(3)
	v_add_f32_e32 v88, v88, v89
	s_waitcnt lgkmcnt(2)
	v_add_f32_e32 v90, v90, v91
	s_waitcnt lgkmcnt(1)
	v_add_f32_e32 v92, v92, v93
	s_waitcnt lgkmcnt(0)
	v_add_f32_e32 v94, v94, v95
	ds_bpermute_b32 v89, v175, v88
	ds_bpermute_b32 v91, v175, v90
	ds_bpermute_b32 v93, v175, v92
	ds_bpermute_b32 v95, v175, v94
	s_and_saveexec_b64 s[14:15], s[6:7]
	s_cbranch_execz .LBB0_679
	s_waitcnt lgkmcnt(3)
	v_add_f32_e32 v88, v88, v89
	v_add_u32_e32 v89, v176, v178
	s_waitcnt lgkmcnt(2)
	v_add_f32_e32 v90, v90, v91
	ds_write_b32 v89, v88 offset:57344
	v_add_u32_e32 v88, v176, v179
	s_waitcnt lgkmcnt(2)
	v_add_f32_e32 v92, v92, v93
	ds_write_b32 v88, v90 offset:57344
	v_add_u32_e32 v88, v176, v180
	s_waitcnt lgkmcnt(2)
	v_add_f32_e32 v94, v94, v95
	ds_write_b32 v88, v92 offset:57344
	v_add_u32_e32 v88, v176, v181
	ds_write_b32 v88, v94 offset:57344
	s_branch .LBB0_679
.LBB0_684:
	v_mov_b32_e32 v144, 0x3f317218
	v_mov_b32_e32 v204, 0x3727c5ac
	s_lshl_b32 s0, s43, 4
	s_add_i32 s0, s0, s2
	s_ashr_i32 s1, s0, 31
	s_lshl_b64 s[0:1], s[0:1], 16
	v_lshlrev_b32_e32 v0, 11, v145
	s_add_u32 s0, s8, s0
	v_lshl_or_b32 v0, v153, 9, v0
	s_addc_u32 s1, s9, s1
	v_or_b32_e32 v2, v151, v0
	s_add_u32 s0, s0, 0xaa00000
	v_ashrrev_i32_e32 v1, 31, v0
	s_addc_u32 s1, s1, 0
	v_ashrrev_i32_e32 v3, 31, v2
	v_lshl_add_u64 v[4:5], v[2:3], 2, s[0:1]
	v_mov_b32_e32 v3, v1
	v_or_b32_e32 v0, 16, v2
	global_store_dword v[4:5], v32, off
	v_lshl_add_u64 v[4:5], v[2:3], 2, s[0:1]
	v_lshl_add_u64 v[6:7], v[0:1], 2, s[0:1]
	v_or_b32_e32 v0, 32, v2
	global_store_dword v[4:5], v33, off offset:512
	global_store_dword v[4:5], v34, off offset:1024
	global_store_dword v[4:5], v35, off offset:1536
	global_store_dword v[4:5], v36, off offset:64
	global_store_dword v[6:7], v37, off offset:512
	global_store_dword v[6:7], v38, off offset:1024
	global_store_dword v[6:7], v39, off offset:1536
	global_store_dword v[4:5], v40, off offset:128
	v_lshl_add_u64 v[6:7], v[0:1], 2, s[0:1]
	v_or_b32_e32 v0, 48, v2
	global_store_dword v[6:7], v41, off offset:512
	global_store_dword v[6:7], v42, off offset:1024
	global_store_dword v[6:7], v43, off offset:1536
	global_store_dword v[4:5], v44, off offset:192
	v_lshl_add_u64 v[6:7], v[0:1], 2, s[0:1]
	v_or_b32_e32 v0, 64, v2
	global_store_dword v[6:7], v45, off offset:512
	global_store_dword v[6:7], v46, off offset:1024
	global_store_dword v[6:7], v47, off offset:1536
	global_store_dword v[4:5], v48, off offset:256
	v_lshl_add_u64 v[6:7], v[0:1], 2, s[0:1]
	v_or_b32_e32 v0, 0x50, v2
	global_store_dword v[6:7], v49, off offset:512
	global_store_dword v[6:7], v50, off offset:1024
	global_store_dword v[6:7], v51, off offset:1536
	global_store_dword v[4:5], v52, off offset:320
	v_lshl_add_u64 v[6:7], v[0:1], 2, s[0:1]
	v_or_b32_e32 v0, 0x60, v2
	global_store_dword v[6:7], v53, off offset:512
	global_store_dword v[6:7], v54, off offset:1024
	global_store_dword v[6:7], v55, off offset:1536
	global_store_dword v[4:5], v56, off offset:384
	v_lshl_add_u64 v[6:7], v[0:1], 2, s[0:1]
	v_or_b32_e32 v0, 0x70, v2
	v_lshl_add_u64 v[0:1], v[0:1], 2, s[0:1]
	global_store_dword v[6:7], v57, off offset:512
	global_store_dword v[6:7], v58, off offset:1024
	global_store_dword v[6:7], v59, off offset:1536
	global_store_dword v[4:5], v60, off offset:448
	global_store_dword v[0:1], v61, off offset:512
	global_store_dword v[0:1], v62, off offset:1024
	global_store_dword v[0:1], v63, off offset:1536
	s_barrier
